# speedup vs baseline: 1.0736x; 1.0055x over previous
; __device__ __forceinline__ f32x16 mfma32(bf16x8 a, bf16x8 b, f32x16 c) { return __builtin_amdgcn_mfma_f32_32x32x16_bf16(a, b, c, 0, 0, 0); }
; __device__ __forceinline__ void attn_block(const Params& p, int bh, int qblk) {
;     ...
;         f32x16 s;
; #pragma unroll
;         for (int i = 0; i < 16; ++i) s[i] = 0.f;
; #pragma unroll
;         for (int ks = 0; ks < 4; ++ks) s = mfma32(kf[ks], qf[ks], s);
;         const bool diag = (kt == qt);
;         float be[16], om[16], wt[16];
; #pragma unroll
;         for (int i = 0; i < 16; ++i) {
;             const float z = s[i] * (0.125f * 1.4426950408889634f);
;             const float e = __builtin_amdgcn_exp2f(-fabsf(z));
;             const float r = __builtin_amdgcn_rcpf(1.0f + e);
;             const float er = e * r;
;             be[i] = z >= 0.f ? r : er;
;             om[i] = z >= 0.f ? er : r;
;             if (diag) {
;                 const int kl = (i & 3) + 8 * (i >> 2) + 4 * hi;
;                 if (kl >= ql) { be[i] = 0.f; om[i] = 1.0f; }
;             }
;         }
;         float run = R;
; #pragma unroll
;         for (int c = 3; c >= 0; --c) {
;             const float g = (om[4 * c] * om[4 * c + 1]) * (om[4 * c + 2] * om[4 * c + 3]);
;             const float pg = __shfl_xor(g, 32);
;             float bt = hi ? run : run * pg;
;             run *= g * pg;
;             wt[4 * c + 3] = be[4 * c + 3] * bt; bt *= om[4 * c + 3];
;             wt[4 * c + 2] = be[4 * c + 2] * bt; bt *= om[4 * c + 2];
;             wt[4 * c + 1] = be[4 * c + 1] * bt; bt *= om[4 * c + 1];
;             wt[4 * c + 0] = be[4 * c + 0] * bt;
;         }
.LBB0_191:
	s_or_b64 exec, exec, s[0:1]
	s_waitcnt vmcnt(1) lgkmcnt(9)
	v_mfma_f32_32x32x16_bf16 v[32:47], v[32:35], v[56:59], 0
	s_cmp_lg_u32 s51, 0
	s_cselect_b64 s[0:1], -1, 0
	v_subrev_u32_e32 v107, 64, v107
	v_subrev_u32_e32 v98, 32, v98
	v_add_u32_e32 v109, 0xfffff000, v109
	s_waitcnt lgkmcnt(8)
	v_mfma_f32_32x32x16_bf16 v[32:47], v[80:83], v[48:51], v[32:47]
	s_waitcnt lgkmcnt(7)
	v_mfma_f32_32x32x16_bf16 v[32:47], v[84:87], v[52:55], v[32:47]
	s_waitcnt vmcnt(0) lgkmcnt(6)
	v_mfma_f32_32x32x16_bf16 v[32:47], v[88:91], v[60:63], v[32:47]
	s_nop 11
	v_mul_f32_e32 v32, 0x3e38aa3b, v32
	v_exp_f32_e64 v80, -|v32|
	v_cmp_le_f32_e32 vcc, 0, v32
	v_mul_f32_e32 v33, 0x3e38aa3b, v33
	v_add_f32_e32 v81, 1.0, v80
	v_rcp_f32_e32 v81, v81
	s_nop 0
	v_mul_f32_e32 v80, v80, v81
	v_cndmask_b32_e32 v32, v80, v81, vcc
	v_cndmask_b32_e32 v80, v81, v80, vcc
	s_or_b64 vcc, s[0:1], s[4:5]
	v_cndmask_b32_e32 v82, 0, v32, vcc
	v_cndmask_b32_e32 v32, 1.0, v80, vcc
	v_exp_f32_e64 v80, -|v33|
	v_cmp_le_f32_e32 vcc, 0, v33
	v_add_f32_e32 v81, 1.0, v80
	v_rcp_f32_e32 v81, v81
	s_nop 0
	v_mul_f32_e32 v80, v80, v81
	v_cndmask_b32_e32 v33, v80, v81, vcc
	v_cndmask_b32_e32 v80, v81, v80, vcc
	s_or_b64 vcc, s[0:1], s[6:7]
	v_cndmask_b32_e32 v83, 0, v33, vcc
	v_mul_f32_e32 v33, 0x3e38aa3b, v34
	v_exp_f32_e64 v34, -|v33|
	v_cndmask_b32_e32 v80, 1.0, v80, vcc
	v_cmp_le_f32_e32 vcc, 0, v33
	v_add_f32_e32 v81, 1.0, v34
	v_rcp_f32_e32 v81, v81
	s_nop 0
	v_mul_f32_e32 v34, v34, v81
	v_cndmask_b32_e32 v33, v34, v81, vcc
	v_cndmask_b32_e32 v34, v81, v34, vcc
	s_or_b64 vcc, s[0:1], s[8:9]
	v_cndmask_b32_e32 v84, 0, v33, vcc
	v_mul_f32_e32 v33, 0x3e38aa3b, v35
	v_cndmask_b32_e32 v81, 1.0, v34, vcc
	v_exp_f32_e64 v34, -|v33|
	v_cmp_le_f32_e32 vcc, 0, v33
	v_add_f32_e32 v35, 1.0, v34
	v_rcp_f32_e32 v35, v35
	s_nop 0
	v_mul_f32_e32 v34, v34, v35
	v_cndmask_b32_e32 v33, v34, v35, vcc
	v_cndmask_b32_e32 v34, v35, v34, vcc
	s_or_b64 vcc, s[0:1], s[10:11]
	v_cndmask_b32_e32 v85, 0, v33, vcc
	v_cndmask_b32_e32 v33, 1.0, v34, vcc
	v_mul_f32_e32 v34, 0x3e38aa3b, v36
	v_exp_f32_e64 v35, -|v34|
	v_cmp_le_f32_e32 vcc, 0, v34
	v_add_f32_e32 v36, 1.0, v35
	v_rcp_f32_e32 v36, v36
	s_nop 0
	v_mul_f32_e32 v35, v35, v36
	v_cndmask_b32_e32 v34, v35, v36, vcc
	v_cndmask_b32_e32 v35, v36, v35, vcc
	s_or_b64 vcc, s[0:1], s[12:13]
	v_cndmask_b32_e32 v86, 0, v34, vcc
	v_cndmask_b32_e32 v34, 1.0, v35, vcc
	v_mul_f32_e32 v35, 0x3e38aa3b, v37
	v_exp_f32_e64 v36, -|v35|
	v_cmp_le_f32_e32 vcc, 0, v35
	v_add_f32_e32 v37, 1.0, v36
	v_rcp_f32_e32 v37, v37
	s_nop 0
	v_mul_f32_e32 v36, v36, v37
	v_cndmask_b32_e32 v35, v36, v37, vcc
	v_cndmask_b32_e32 v36, v37, v36, vcc
	s_or_b64 vcc, s[0:1], s[14:15]
	v_cndmask_b32_e32 v87, 0, v35, vcc
	v_mul_f32_e32 v35, 0x3e38aa3b, v38
	v_exp_f32_e64 v37, -|v35|
	v_cndmask_b32_e32 v36, 1.0, v36, vcc
	v_cmp_le_f32_e32 vcc, 0, v35
	v_add_f32_e32 v38, 1.0, v37
	v_rcp_f32_e32 v38, v38
	s_nop 0
	v_mul_f32_e32 v37, v37, v38
	v_cndmask_b32_e32 v35, v37, v38, vcc
	v_cndmask_b32_e32 v37, v38, v37, vcc
	s_or_b64 vcc, s[0:1], s[16:17]
	v_cndmask_b32_e32 v88, 0, v35, vcc
	v_mul_f32_e32 v35, 0x3e38aa3b, v39
	v_exp_f32_e64 v38, -|v35|
	v_cndmask_b32_e32 v37, 1.0, v37, vcc
	v_cmp_le_f32_e32 vcc, 0, v35
	v_add_f32_e32 v39, 1.0, v38
	v_rcp_f32_e32 v39, v39
	s_nop 0
	v_mul_f32_e32 v38, v38, v39
	v_cndmask_b32_e32 v35, v38, v39, vcc
	v_cndmask_b32_e32 v38, v39, v38, vcc
	s_or_b64 vcc, s[0:1], s[18:19]
	v_cndmask_b32_e32 v89, 0, v35, vcc
	v_cndmask_b32_e32 v35, 1.0, v38, vcc
	v_mul_f32_e32 v38, 0x3e38aa3b, v40
	v_exp_f32_e64 v39, -|v38|
	v_cmp_le_f32_e32 vcc, 0, v38
	v_add_f32_e32 v40, 1.0, v39
	v_rcp_f32_e32 v40, v40
	s_nop 0
	v_mul_f32_e32 v39, v39, v40
	v_cndmask_b32_e32 v38, v39, v40, vcc
	v_cndmask_b32_e32 v39, v40, v39, vcc
	s_or_b64 vcc, s[0:1], s[20:21]
	v_cndmask_b32_e32 v90, 0, v38, vcc
	v_cndmask_b32_e32 v38, 1.0, v39, vcc
	v_mul_f32_e32 v39, 0x3e38aa3b, v41
	v_exp_f32_e64 v40, -|v39|
	v_cmp_le_f32_e32 vcc, 0, v39
	v_add_f32_e32 v41, 1.0, v40
	v_rcp_f32_e32 v41, v41
	s_nop 0
	v_mul_f32_e32 v40, v40, v41
	v_cndmask_b32_e32 v39, v40, v41, vcc
	v_cndmask_b32_e32 v40, v41, v40, vcc
	s_or_b64 vcc, s[0:1], s[22:23]
	v_cndmask_b32_e32 v91, 0, v39, vcc
	v_mul_f32_e32 v39, 0x3e38aa3b, v42
	v_exp_f32_e64 v41, -|v39|
	v_cndmask_b32_e32 v40, 1.0, v40, vcc
	v_cmp_le_f32_e32 vcc, 0, v39
	v_add_f32_e32 v42, 1.0, v41
	v_rcp_f32_e32 v42, v42
	s_nop 0
	v_mul_f32_e32 v41, v41, v42
	v_cndmask_b32_e32 v39, v41, v42, vcc
	v_cndmask_b32_e32 v41, v42, v41, vcc
	s_or_b64 vcc, s[0:1], s[24:25]
	v_cndmask_b32_e32 v99, 0, v39, vcc
	v_mul_f32_e32 v39, 0x3e38aa3b, v43
	v_exp_f32_e64 v42, -|v39|
	v_cndmask_b32_e32 v41, 1.0, v41, vcc
	v_cmp_le_f32_e32 vcc, 0, v39
	v_add_f32_e32 v43, 1.0, v42
	v_rcp_f32_e32 v43, v43
	s_nop 0
	v_mul_f32_e32 v42, v42, v43
	v_cndmask_b32_e32 v39, v42, v43, vcc
	v_cndmask_b32_e32 v42, v43, v42, vcc
	s_or_b64 vcc, s[0:1], s[26:27]
	v_cndmask_b32_e32 v111, 0, v39, vcc
	v_cndmask_b32_e32 v39, 1.0, v42, vcc
	v_mul_f32_e32 v42, 0x3e38aa3b, v44
	v_exp_f32_e64 v43, -|v42|
	v_cmp_le_f32_e32 vcc, 0, v42
	v_add_f32_e32 v44, 1.0, v43
	v_rcp_f32_e32 v44, v44
	s_nop 0
	v_mul_f32_e32 v43, v43, v44
	v_cndmask_b32_e32 v42, v43, v44, vcc
	v_cndmask_b32_e32 v43, v44, v43, vcc
	s_or_b64 vcc, s[0:1], s[28:29]
	v_cndmask_b32_e32 v100, 0, v42, vcc
	v_cndmask_b32_e32 v42, 1.0, v43, vcc
	v_mul_f32_e32 v43, 0x3e38aa3b, v45
	v_exp_f32_e64 v44, -|v43|
	v_cmp_le_f32_e32 vcc, 0, v43
	v_add_f32_e32 v45, 1.0, v44
	v_rcp_f32_e32 v45, v45
	s_nop 0
	v_mul_f32_e32 v44, v44, v45
	v_cndmask_b32_e32 v43, v44, v45, vcc
	v_cndmask_b32_e32 v44, v45, v44, vcc
	s_or_b64 vcc, s[0:1], s[30:31]
	v_cndmask_b32_e32 v112, 0, v43, vcc
	v_mul_f32_e32 v43, 0x3e38aa3b, v46
	v_exp_f32_e64 v45, -|v43|
	v_cndmask_b32_e32 v44, 1.0, v44, vcc
	v_cmp_le_f32_e32 vcc, 0, v43
	v_add_f32_e32 v46, 1.0, v45
	v_rcp_f32_e32 v46, v46
	s_nop 0
	v_mul_f32_e32 v45, v45, v46
	v_cndmask_b32_e32 v43, v45, v46, vcc
	v_cndmask_b32_e32 v45, v46, v45, vcc
	s_or_b64 vcc, s[0:1], s[34:35]
	v_cndmask_b32_e32 v113, 0, v43, vcc
	v_mul_f32_e32 v43, 0x3e38aa3b, v47
	v_exp_f32_e64 v46, -|v43|
	v_cndmask_b32_e32 v45, 1.0, v45, vcc
	v_cmp_le_f32_e32 vcc, 0, v43
	v_add_f32_e32 v47, 1.0, v46
	v_rcp_f32_e32 v47, v47
	s_nop 0
	v_mul_f32_e32 v46, v46, v47
	v_cndmask_b32_e32 v43, v46, v47, vcc
	v_cndmask_b32_e32 v46, v47, v46, vcc
	s_or_b64 vcc, s[36:37], s[0:1]
	v_cndmask_b32_e32 v114, 0, v43, vcc
	v_cndmask_b32_e32 v43, 1.0, v46, vcc
	v_pk_mul_f32 v[46:47], v[44:45], v[42:43]
	s_mov_b32 s0, 0x114ad2f8
	v_pk_mul_f32 v[46:47], v[46:47], v[46:47] op_sel:[0,1] op_sel_hi:[1,0]
	v_mov_b32_e32 v116, v46
	v_mov_b32_e32 v117, v46
	s_nop 1
	v_permlane32_swap_b32_e32 v116, v117
	v_cndmask_b32_e64 v47, v116, v117, s[38:39]
	s_waitcnt lgkmcnt(0)
; __device__ __forceinline__ f32x16 mfma32(bf16x8 a, bf16x8 b, f32x16 c) { return __builtin_amdgcn_mfma_f32_32x32x16_bf16(a, b, c, 0, 0, 0); }
; __device__ __forceinline__ void attn_block(const Params& p, int bh, int qblk) {
;     ...
;         float run = R;
; #pragma unroll
;         for (int c = 3; c >= 0; --c) {
;             const float g = (om[4 * c] * om[4 * c + 1]) * (om[4 * c + 2] * om[4 * c + 3]);
;             const float pg = __shfl_xor(g, 32);
;             float bt = hi ? run : run * pg;
;             run *= g * pg;
;             wt[4 * c + 3] = be[4 * c + 3] * bt; bt *= om[4 * c + 3];
;             wt[4 * c + 2] = be[4 * c + 2] * bt; bt *= om[4 * c + 2];
;             wt[4 * c + 1] = be[4 * c + 1] * bt; bt *= om[4 * c + 1];
;             wt[4 * c + 0] = be[4 * c + 0] * bt;
;         }
;         R = run;
;         bf16x8 pf[2];
; #pragma unroll
;         for (int kk = 0; kk < 2; ++kk) {
;             uint4 c4 = make_uint4(pk2(wt[8 * kk], wt[8 * kk + 1]), pk2(wt[8 * kk + 2], wt[8 * kk + 3]),
;                                   pk2(wt[8 * kk + 4], wt[8 * kk + 5]), pk2(wt[8 * kk + 6], wt[8 * kk + 7]));
;             pf[kk] = __builtin_bit_cast(bf16x8, c4);
;         }
;         o0 = mfma32(vc[0][0], pf[0], o0); o0 = mfma32(vc[0][1], pf[1], o0);
;         o1 = mfma32(vc[1][0], pf[0], o1); o1 = mfma32(vc[1][1], pf[1], o1);
;         if (__all(R < 1.6e-28f)) break;
	v_mul_f32_e32 v42, v101, v47
	v_cndmask_b32_e64 v42, v101, v42, s[38:39]
	v_mul_f32_e32 v114, v42, v114
	v_mul_f32_e32 v42, v42, v43
	v_mul_f32_e32 v113, v113, v42
	v_mul_f32_e32 v42, v45, v42
	v_mul_f32_e32 v112, v112, v42
	v_mul_f32_e32 v42, v44, v42
	v_mul_f32_e32 v115, v100, v42
	v_pk_mul_f32 v[42:43], v[40:41], v[38:39]
	v_mov_b32_e32 v45, v46
	v_mov_b32_e32 v44, v42
	v_mov_b32_e32 v46, v43
	v_pk_mul_f32 v[42:43], v[44:45], v[46:47]
	v_mov_b32_e32 v116, v42
	v_mov_b32_e32 v117, v42
	s_nop 1
	v_permlane32_swap_b32_e32 v116, v117
	v_cndmask_b32_e64 v100, v116, v117, s[38:39]
	s_waitcnt lgkmcnt(0)
	v_pk_mul_f32 v[42:43], v[42:43], v[100:101]
	s_nop 0
	v_mul_f32_e32 v38, v43, v100
	v_cndmask_b32_e64 v38, v43, v38, s[38:39]
	v_mul_f32_e32 v44, v111, v38
	v_mul_f32_e32 v38, v39, v38
	v_mul_f32_e32 v45, v99, v38
	v_mul_f32_e32 v38, v41, v38
	v_mul_f32_e32 v46, v91, v38
	v_mul_f32_e32 v38, v40, v38
	v_mul_f32_e32 v47, v90, v38
	v_pk_mul_f32 v[38:39], v[36:37], v[34:35]
	v_mov_b32_e32 v41, v42
	v_mov_b32_e32 v40, v38
	v_mov_b32_e32 v42, v39
	v_pk_mul_f32 v[38:39], v[40:41], v[42:43]
	v_mov_b32_e32 v116, v38
	v_mov_b32_e32 v117, v38
	s_nop 1
	v_permlane32_swap_b32_e32 v116, v117
	v_cndmask_b32_e64 v41, v116, v117, s[38:39]
	s_waitcnt lgkmcnt(0)
	v_mul_f32_e32 v34, v39, v41
	v_cndmask_b32_e64 v34, v39, v34, s[38:39]
	v_mul_f32_e32 v42, v89, v34
	v_mul_f32_e32 v34, v35, v34
	v_mul_f32_e32 v43, v88, v34
	v_mul_f32_e32 v34, v37, v34
	v_mul_f32_e32 v87, v87, v34
	v_mul_f32_e32 v34, v36, v34
	v_mul_f32_e32 v86, v86, v34
	v_pk_mul_f32 v[34:35], v[80:81], v[32:33]
	v_mov_b32_e32 v37, v38
	v_mov_b32_e32 v36, v34
	v_mov_b32_e32 v40, v35
	v_pk_mul_f32 v[34:35], v[36:37], v[40:41]
	v_mov_b32_e32 v116, v34
	v_mov_b32_e32 v117, v34
	s_nop 1
	v_permlane32_swap_b32_e32 v116, v117
	v_cndmask_b32_e64 v38, v116, v117, s[38:39]
	v_cvt_pk_bf16_f32 v36, v47, v46
	v_cvt_pk_bf16_f32 v37, v45, v44
	s_waitcnt lgkmcnt(0)
	v_pk_mul_f32 v[40:41], v[34:35], v[38:39]
	s_nop 0
	v_mul_f32_e32 v32, v41, v38
	v_cndmask_b32_e64 v32, v41, v32, s[38:39]
	v_mul_f32_e32 v34, v85, v32
	v_mul_f32_e32 v32, v33, v32
	v_mul_f32_e32 v33, v84, v32
	v_mul_f32_e32 v32, v81, v32
	v_mul_f32_e32 v35, v83, v32
	v_mul_f32_e32 v32, v80, v32
	v_mul_f32_e32 v32, v82, v32
	v_cvt_pk_bf16_f32 v32, v32, v35
	v_cvt_pk_bf16_f32 v33, v33, v34
	v_cvt_pk_bf16_f32 v34, v86, v87
	v_cvt_pk_bf16_f32 v35, v43, v42
	v_cvt_pk_bf16_f32 v38, v115, v112
	v_cvt_pk_bf16_f32 v39, v113, v114
	v_mfma_f32_32x32x16_bf16 v[16:31], v[72:75], v[32:35], v[16:31]
	v_mul_f32_e32 v101, v40, v41
	v_cmp_gt_f32_e32 vcc, s0, v101
	s_cmp_eq_u64 vcc, exec
	s_cselect_b64 s[0:1], -1, 0
	v_cmp_eq_u32_e32 vcc, s51, v106
	s_or_b64 s[0:1], vcc, s[0:1]
	s_add_i32 s51, s51, 1
	v_mfma_f32_32x32x16_bf16 v[0:15], v[68:71], v[32:35], v[0:15]
	s_and_b64 s[0:1], exec, s[0:1]
	s_or_b64 s[2:3], s[0:1], s[2:3]
	v_mfma_f32_32x32x16_bf16 v[16:31], v[64:67], v[36:39], v[16:31]
	v_mfma_f32_32x32x16_bf16 v[0:15], v[76:79], v[36:39], v[0:15]
	s_andn2_b64 exec, exec, s[2:3]
	s_cbranch_execz .LBB0_187

; __device__ __forceinline__ void pool_item(const Params& p, int l, int item) {
;     ...
;     for (int idx = tid; idx < 2048; idx += NT) {
;         int n = idx >> 4, c = idx & 15;
;         uint4 v = *reinterpret_cast<const uint4*>(wp + n * 128 + c * 8);
;         *reinterpret_cast<uint4*>(lds + 65536 + n * 256 + ((c ^ (n & 15)) * 16)) = v;
;     }
.LBB0_206:
	v_lshrrev_b32_e32 v222, 4, v214
	v_and_b32_e32 v223, 15, v214
	v_lshlrev_b32_e32 v224, 8, v222
	v_lshl_or_b32 v225, v223, 4, v224
	v_xor_b32_e32 v226, v222, v223
	v_and_b32_e32 v226, 15, v226
	v_lshl_add_u32 v226, v226, 4, v224
	v_add_u32_e32 v226, s90, v226
	global_load_dwordx4 v[236:239], v225, s[2:3]
	v_add_u32_e32 v227, 0x2000, v225
	global_load_dwordx4 v[240:243], v227, s[2:3]
	v_add_u32_e32 v227, 0x4000, v225
	global_load_dwordx4 v[244:247], v227, s[2:3]
	v_add_u32_e32 v227, 0x6000, v225
	global_load_dwordx4 v[248:251], v227, s[2:3]
	s_waitcnt vmcnt(3)
	ds_write_b128 v226, v[236:239]
	s_waitcnt vmcnt(2)
	ds_write_b128 v226, v[240:243] offset:8192
	s_waitcnt vmcnt(1)
	ds_write_b128 v226, v[244:247] offset:16384
	s_waitcnt vmcnt(0)
	ds_write_b128 v226, v[248:251] offset:24576
	s_or_b64 exec, exec, s[6:7]

; __global__ void __launch_bounds__(512, 2) mega(Params p) {
;     cg::grid_group grid = cg::this_grid();
;     ...
;     phase_prep(p);
;     if (p.never) grid.sync();
;     xcd_barrier(xb, 0u);
; #pragma unroll 1
;     for (int l = 0; l < 2; ++l) {
;         const unsigned e0 = 1u + 5u * (unsigned)l;
;         phase_A(p, l);
;         xcd_barrier(xb, e0);
;         phase_B(p, l);
;         xcd_barrier(xb, e0 + 1u);
;         phase_GC(p, l);
;         xcd_barrier(xb, e0 + 2u);
;         phase_D(p, l);
;         xcd_barrier(xb, e0 + 3u);
;         phase_E(p, l);
;         if (l == 0) xcd_barrier(xb, e0 + 4u);
;     }
; }
	.amdhsa_kernel _Z4mega6Params
		.amdhsa_group_segment_fixed_size 0
		.amdhsa_private_segment_fixed_size 0
		.amdhsa_kernarg_size 400
		.amdhsa_user_sgpr_count 2
		.amdhsa_user_sgpr_dispatch_ptr 0
		.amdhsa_user_sgpr_queue_ptr 0
		.amdhsa_user_sgpr_kernarg_segment_ptr 1
		.amdhsa_user_sgpr_dispatch_id 0
		.amdhsa_user_sgpr_kernarg_preload_length 0
		.amdhsa_user_sgpr_kernarg_preload_offset 0
		.amdhsa_user_sgpr_private_segment_size 0
		.amdhsa_uses_dynamic_stack 0
		.amdhsa_enable_private_segment 0
		.amdhsa_system_sgpr_workgroup_id_x 1
		.amdhsa_system_sgpr_workgroup_id_y 0
		.amdhsa_system_sgpr_workgroup_id_z 0
		.amdhsa_system_sgpr_workgroup_info 0
		.amdhsa_system_vgpr_workitem_id 2
		.amdhsa_next_free_vgpr 252
		.amdhsa_next_free_sgpr 102
		.amdhsa_accum_offset 252
		.amdhsa_reserve_vcc 1
		.amdhsa_float_round_mode_32 0
		.amdhsa_float_round_mode_16_64 0
		.amdhsa_float_denorm_mode_32 3
		.amdhsa_float_denorm_mode_16_64 3
		.amdhsa_dx10_clamp 1
		.amdhsa_ieee_mode 1
		.amdhsa_fp16_overflow 0
		.amdhsa_tg_split 0
		.amdhsa_exception_fp_ieee_invalid_op 0
		.amdhsa_exception_fp_denorm_src 0
		.amdhsa_exception_fp_ieee_div_zero 0
		.amdhsa_exception_fp_ieee_overflow 0
		.amdhsa_exception_fp_ieee_underflow 0
		.amdhsa_exception_fp_ieee_inexact 0
		.amdhsa_exception_int_div_zero 0
	.end_amdhsa_kernel

; __global__ void __launch_bounds__(512, 2) mega(Params p) {
.Lfunc_end0:
	.size	_Z4mega6Params, .Lfunc_end0-_Z4mega6Params
	.set _Z4mega6Params.num_vgpr, 252
	.set _Z4mega6Params.num_agpr, 0
	.set _Z4mega6Params.numbered_sgpr, 98
	.set _Z4mega6Params.num_named_barrier, 0
	.set _Z4mega6Params.private_seg_size, 0
	.set _Z4mega6Params.uses_vcc, 1
	.set _Z4mega6Params.uses_flat_scratch, 0
	.set _Z4mega6Params.has_dyn_sized_stack, 0
	.set _Z4mega6Params.has_recursion, 0
	.set _Z4mega6Params.has_indirect_call, 0

; __global__ void __launch_bounds__(512, 2) mega(Params p) {
amdhsa.kernels:
  - .agpr_count:     0
    .args:
      - .offset:         0
        .size:           144
        .value_kind:     by_value
      - .offset:         144
        .size:           4
        .value_kind:     hidden_block_count_x
      - .offset:         148
        .size:           4
        .value_kind:     hidden_block_count_y
      - .offset:         152
        .size:           4
        .value_kind:     hidden_block_count_z
      - .offset:         156
        .size:           2
        .value_kind:     hidden_group_size_x
      - .offset:         158
        .size:           2
        .value_kind:     hidden_group_size_y
      - .offset:         160
        .size:           2
        .value_kind:     hidden_group_size_z
      - .offset:         162
        .size:           2
        .value_kind:     hidden_remainder_x
      - .offset:         164
        .size:           2
        .value_kind:     hidden_remainder_y
      - .offset:         166
        .size:           2
        .value_kind:     hidden_remainder_z
      - .offset:         184
        .size:           8
        .value_kind:     hidden_global_offset_x
      - .offset:         192
        .size:           8
        .value_kind:     hidden_global_offset_y
      - .offset:         200
        .size:           8
        .value_kind:     hidden_global_offset_z
      - .offset:         208
        .size:           2
        .value_kind:     hidden_grid_dims
      - .offset:         232
        .size:           8
        .value_kind:     hidden_multigrid_sync_arg
      - .offset:         264
        .size:           4
        .value_kind:     hidden_dynamic_lds_size
    .group_segment_fixed_size: 0
    .kernarg_segment_align: 8
    .kernarg_segment_size: 400
    .language:       OpenCL C
    .language_version:
      - 2
      - 0
    .max_flat_workgroup_size: 512
    .name:           _Z4mega6Params
    .private_segment_fixed_size: 0
    .sgpr_count:     108
    .sgpr_spill_count: 64
    .symbol:         _Z4mega6Params.kd
    .uniform_work_group_size: 1
    .uses_dynamic_stack: false
    .vgpr_count:     252
    .vgpr_spill_count: 0
    .wavefront_size: 64
